# GEMM2 MG stores sc1 (write-through) on top of h1pf
# baseline (speedup 1.0000x reference)
;     __device__ __forceinline__ void operator()(f32x4 (&acc)[2][2][4][2], const Unit& u, int wr, int wc, int fr, int fq) const {
;         const int row0 = u.pm * BM + wr * 64 + fr, col0 = u.pn * BM + wc * 32 + 8 * fq;
;         const h16* gbase = PG + (size_t)(u.pm * 32 + 2 * u.pn) * 65536 + (u.half == 0 ? 0 : 32768) + (wr * 4 + wc) * 512 + (fq * 16 + fr) * 8;
; #pragma unroll
;         for (int ai = 0; ai < 2; ++ai) {
;             h16x8 gt[4][2];
; #pragma unroll
;             for (int m = 0; m < 4; ++m)
; #pragma unroll
;                 for (int bj = 0; bj < 2; ++bj) gt[m][bj] = *(const h16x8*)(gbase + (size_t)bj * 65536 + (ai * 4 + m) * 4096);
;             if (u.half == 0) {
.LBB0_474:
	s_lshl_b32 s4, s44, 5
	s_lshl_b32 s5, s45, 1
	s_add_i32 s4, s4, s5
	s_ashr_i32 s5, s4, 31
	s_lshl_b64 s[4:5], s[4:5], 17
	s_add_u32 s27, s61, s4
	s_addc_u32 s29, s62, s5
	s_cmp_lg_u32 s80, 0
	s_cselect_b64 s[46:47], -1, 0
	s_cmp_eq_u32 s80, 0
	s_cselect_b64 s[4:5], -1, 0
	s_and_b64 s[4:5], s[4:5], exec
	s_cselect_b32 s48, 0, 0x10000
	s_add_u32 s27, s27, s48
	s_addc_u32 s29, s29, 0
	s_add_u32 s48, s27, s18
	s_addc_u32 s49, s29, s19
	v_lshl_add_u64 v[146:147], s[48:49], 0, v[132:133]
	v_add_co_u32_e32 v142, vcc, s72, v146
	global_load_dwordx4 v[148:151], v132, s[48:49] nt
	s_nop 0
	v_addc_co_u32_e32 v143, vcc, 0, v147, vcc
	global_load_dwordx4 v[152:155], v[142:143], off nt
	v_add_co_u32_e32 v142, vcc, s59, v146
	v_lshl_add_u32 v144, s44, 8, v213
	s_nop 0
	v_addc_co_u32_e32 v143, vcc, 0, v147, vcc
	global_load_dwordx4 v[156:159], v[142:143], off nt
	v_add_co_u32_e32 v142, vcc, 0x22000, v146
	v_ashrrev_i32_e32 v145, 31, v144
	s_nop 0
	v_addc_co_u32_e32 v143, vcc, 0, v147, vcc
	global_load_dwordx4 v[160:163], v[142:143], off nt
	v_add_co_u32_e32 v142, vcc, s60, v146
	s_nop 1
	v_addc_co_u32_e32 v143, vcc, 0, v147, vcc
	global_load_dwordx4 v[164:167], v[142:143], off nt
	v_add_co_u32_e32 v142, vcc, 0x24000, v146
	s_nop 1
	v_addc_co_u32_e32 v143, vcc, 0, v147, vcc
	global_load_dwordx4 v[218:221], v[142:143], off nt
	v_add_co_u32_e32 v142, vcc, 0x6000, v146
	s_nop 1
	v_addc_co_u32_e32 v143, vcc, 0, v147, vcc
	global_load_dwordx4 v[222:225], v[142:143], off nt
	v_add_co_u32_e32 v142, vcc, 0x26000, v146
	s_nop 1
	v_addc_co_u32_e32 v143, vcc, 0, v147, vcc
	global_load_dwordx4 v[226:229], v[142:143], off nt
	s_waitcnt vmcnt(4)
	v_cvt_f32_f16_sdwa v205, v150 dst_sel:DWORD dst_unused:UNUSED_PAD src0_sel:WORD_1
	v_cvt_f32_f16_e32 v208, v148
	v_cvt_f32_f16_e32 v204, v150
	v_cvt_f32_f16_sdwa v209, v148 dst_sel:DWORD dst_unused:UNUSED_PAD src0_sel:WORD_1
	v_cvt_f32_f16_e32 v210, v149
	v_cvt_f32_f16_e32 v206, v151
	v_cvt_f32_f16_sdwa v211, v149 dst_sel:DWORD dst_unused:UNUSED_PAD src0_sel:WORD_1
	v_cvt_f32_f16_sdwa v207, v151 dst_sel:DWORD dst_unused:UNUSED_PAD src0_sel:WORD_1
	v_cvt_f32_f16_e32 v200, v152
	v_cvt_f32_f16_e32 v196, v154
	v_cvt_f32_f16_sdwa v201, v152 dst_sel:DWORD dst_unused:UNUSED_PAD src0_sel:WORD_1
	v_cvt_f32_f16_sdwa v197, v154 dst_sel:DWORD dst_unused:UNUSED_PAD src0_sel:WORD_1
	v_cvt_f32_f16_e32 v202, v153
	v_cvt_f32_f16_e32 v198, v155
	v_cvt_f32_f16_sdwa v203, v153 dst_sel:DWORD dst_unused:UNUSED_PAD src0_sel:WORD_1
	v_cvt_f32_f16_sdwa v199, v155 dst_sel:DWORD dst_unused:UNUSED_PAD src0_sel:WORD_1
	v_cvt_f32_f16_e32 v192, v156
	v_cvt_f32_f16_e32 v188, v158
	v_cvt_f32_f16_sdwa v193, v156 dst_sel:DWORD dst_unused:UNUSED_PAD src0_sel:WORD_1
	v_cvt_f32_f16_sdwa v189, v158 dst_sel:DWORD dst_unused:UNUSED_PAD src0_sel:WORD_1
	v_cvt_f32_f16_e32 v194, v157
	v_cvt_f32_f16_e32 v190, v159
	v_cvt_f32_f16_sdwa v195, v157 dst_sel:DWORD dst_unused:UNUSED_PAD src0_sel:WORD_1
	v_cvt_f32_f16_sdwa v191, v159 dst_sel:DWORD dst_unused:UNUSED_PAD src0_sel:WORD_1
	v_cvt_f32_f16_e32 v184, v160
	v_cvt_f32_f16_e32 v180, v162
	v_cvt_f32_f16_sdwa v185, v160 dst_sel:DWORD dst_unused:UNUSED_PAD src0_sel:WORD_1
	v_cvt_f32_f16_sdwa v181, v162 dst_sel:DWORD dst_unused:UNUSED_PAD src0_sel:WORD_1
	v_cvt_f32_f16_e32 v186, v161
	v_cvt_f32_f16_e32 v182, v163
	v_cvt_f32_f16_sdwa v187, v161 dst_sel:DWORD dst_unused:UNUSED_PAD src0_sel:WORD_1
	v_cvt_f32_f16_sdwa v183, v163 dst_sel:DWORD dst_unused:UNUSED_PAD src0_sel:WORD_1
	v_lshl_or_b32 v142, s45, 8, v215
	s_mov_b64 s[44:45], -1
	v_ashrrev_i32_e32 v143, 31, v142
	s_mov_b64 vcc, s[4:5]
	s_waitcnt vmcnt(3)
	v_cvt_f32_f16_e32 v176, v164
	v_cvt_f32_f16_e32 v172, v166
	v_cvt_f32_f16_sdwa v177, v164 dst_sel:DWORD dst_unused:UNUSED_PAD src0_sel:WORD_1
	v_cvt_f32_f16_sdwa v173, v166 dst_sel:DWORD dst_unused:UNUSED_PAD src0_sel:WORD_1
	v_cvt_f32_f16_e32 v178, v165
	v_cvt_f32_f16_e32 v174, v167
	v_cvt_f32_f16_sdwa v179, v165 dst_sel:DWORD dst_unused:UNUSED_PAD src0_sel:WORD_1
	v_cvt_f32_f16_sdwa v175, v167 dst_sel:DWORD dst_unused:UNUSED_PAD src0_sel:WORD_1
	s_waitcnt vmcnt(2)
	v_cvt_f32_f16_e32 v168, v218
	v_cvt_f32_f16_e32 v164, v220
	v_cvt_f32_f16_sdwa v169, v218 dst_sel:DWORD dst_unused:UNUSED_PAD src0_sel:WORD_1
	v_cvt_f32_f16_sdwa v165, v220 dst_sel:DWORD dst_unused:UNUSED_PAD src0_sel:WORD_1
	v_cvt_f32_f16_e32 v170, v219
	v_cvt_f32_f16_e32 v166, v221
	v_cvt_f32_f16_sdwa v171, v219 dst_sel:DWORD dst_unused:UNUSED_PAD src0_sel:WORD_1
	v_cvt_f32_f16_sdwa v167, v221 dst_sel:DWORD dst_unused:UNUSED_PAD src0_sel:WORD_1
	s_waitcnt vmcnt(1)
	v_cvt_f32_f16_e32 v160, v222
	v_cvt_f32_f16_e32 v156, v224
	v_cvt_f32_f16_sdwa v161, v222 dst_sel:DWORD dst_unused:UNUSED_PAD src0_sel:WORD_1
	v_cvt_f32_f16_sdwa v157, v224 dst_sel:DWORD dst_unused:UNUSED_PAD src0_sel:WORD_1
	v_cvt_f32_f16_e32 v162, v223
	v_cvt_f32_f16_e32 v158, v225
	v_cvt_f32_f16_sdwa v163, v223 dst_sel:DWORD dst_unused:UNUSED_PAD src0_sel:WORD_1
	v_cvt_f32_f16_sdwa v159, v225 dst_sel:DWORD dst_unused:UNUSED_PAD src0_sel:WORD_1
	s_waitcnt vmcnt(0)
	v_cvt_f32_f16_e32 v152, v226
	v_cvt_f32_f16_e32 v148, v228
	v_cvt_f32_f16_sdwa v153, v226 dst_sel:DWORD dst_unused:UNUSED_PAD src0_sel:WORD_1
	v_cvt_f32_f16_sdwa v149, v228 dst_sel:DWORD dst_unused:UNUSED_PAD src0_sel:WORD_1
	v_cvt_f32_f16_e32 v154, v227
	v_cvt_f32_f16_e32 v150, v229
	v_cvt_f32_f16_sdwa v155, v227 dst_sel:DWORD dst_unused:UNUSED_PAD src0_sel:WORD_1
	v_cvt_f32_f16_sdwa v151, v229 dst_sel:DWORD dst_unused:UNUSED_PAD src0_sel:WORD_1
	s_cbranch_vccnz .LBB0_476
;     __device__ __forceinline__ void operator()(f32x4 (&acc)[2][2][4][2], const Unit& u, int wr, int wc, int fr, int fq) const {
;     ...
;                 for (int m = 0; m < 4; ++m) { const size_t row = (size_t)(row0 + ai * HALF + m * 16);
; #pragma unroll
;                     for (int bj = 0; bj < 2; ++bj) { const int col = col0 + bj * HALF;
;                         float o[8];
; #pragma unroll
;                         for (int j = 0; j < 4; ++j) { o[j] = acc[ai][bj][m][0][j] * (float)gt[m][bj][j]; o[4 + j] = acc[ai][bj][m][1][j] * (float)gt[m][bj][4 + j]; }
;                         u32x4 w; w.x = pkg(o[0], o[1]); w.y = pkg(o[2], o[3]); w.z = pkg(o[4], o[5]); w.w = pkg(o[6], o[7]);
;                         *(u32x4*)(MG + row * D + col) = w; } }
	v_lshlrev_b64 v[222:223], 13, v[144:145]
	v_mul_f32_e32 v220, v120, v204
	v_mul_f32_e32 v221, v121, v205
	v_mul_f32_e32 v219, v126, v210
	v_mul_f32_e32 v224, v122, v206
	v_mul_f32_e32 v225, v127, v211
	v_mul_f32_e32 v218, v125, v209
	v_mul_f32_e32 v226, v123, v207
	v_cvt_pk_bf16_f32 v219, v219, v225
	v_cvt_pk_bf16_f32 v220, v220, v221
	v_cvt_pk_bf16_f32 v221, v224, v226
	v_lshl_add_u64 v[222:223], s[12:13], 0, v[222:223]
	v_lshlrev_b64 v[224:225], 1, v[142:143]
	v_mul_f32_e32 v217, v124, v208
	v_cvt_pk_bf16_f32 v218, v217, v218
	v_lshl_add_u64 v[222:223], v[222:223], 0, v[224:225]
	global_store_dwordx4 v[222:223], v[218:221], off sc1
	v_mul_f32_e32 v217, v92, v200
	v_mul_f32_e32 v226, v90, v198
	v_mul_f32_e32 v218, v93, v201
	v_mul_f32_e32 v220, v88, v196
	v_mul_f32_e32 v221, v89, v197
	v_mul_f32_e32 v219, v94, v202
	v_cvt_pk_bf16_f32 v218, v217, v218
	v_mul_f32_e32 v227, v95, v203
	v_mul_f32_e32 v228, v91, v199
	v_cvt_pk_bf16_f32 v219, v219, v227
	v_cvt_pk_bf16_f32 v220, v220, v221
	v_cvt_pk_bf16_f32 v221, v226, v228
	global_store_dwordx4 v[222:223], v[218:221], off offset:256 sc1
	v_mul_f32_e32 v217, v116, v192
	v_mul_f32_e32 v226, v114, v190
	v_or_b32_e32 v218, 16, v144
	v_ashrrev_i32_e32 v219, 31, v218
	v_lshlrev_b64 v[222:223], 13, v[218:219]
	v_mul_f32_e32 v218, v117, v193
	v_lshl_add_u64 v[222:223], s[12:13], 0, v[222:223]
	v_mul_f32_e32 v220, v112, v188
	v_mul_f32_e32 v221, v113, v189
	v_mul_f32_e32 v219, v118, v194
	v_cvt_pk_bf16_f32 v218, v217, v218
	v_lshl_add_u64 v[222:223], v[222:223], 0, v[224:225]
	v_mul_f32_e32 v227, v119, v195
	v_mul_f32_e32 v228, v115, v191
	v_cvt_pk_bf16_f32 v219, v219, v227
	v_cvt_pk_bf16_f32 v220, v220, v221
	v_cvt_pk_bf16_f32 v221, v226, v228
	global_store_dwordx4 v[222:223], v[218:221], off sc1
	v_mul_f32_e32 v217, v84, v184
	v_mul_f32_e32 v226, v82, v182
	v_mul_f32_e32 v218, v85, v185
	v_mul_f32_e32 v220, v80, v180
	v_mul_f32_e32 v221, v81, v181
	v_mul_f32_e32 v219, v86, v186
	v_cvt_pk_bf16_f32 v218, v217, v218
	v_mul_f32_e32 v227, v87, v187
	v_mul_f32_e32 v228, v83, v183
	v_cvt_pk_bf16_f32 v219, v219, v227
	v_cvt_pk_bf16_f32 v220, v220, v221
	v_cvt_pk_bf16_f32 v221, v226, v228
	global_store_dwordx4 v[222:223], v[218:221], off offset:256 sc1
	v_mul_f32_e32 v217, v108, v176
	v_mul_f32_e32 v226, v106, v174
	v_or_b32_e32 v218, 32, v144
	v_ashrrev_i32_e32 v219, 31, v218
	v_lshlrev_b64 v[222:223], 13, v[218:219]
	v_mul_f32_e32 v218, v109, v177
	v_lshl_add_u64 v[222:223], s[12:13], 0, v[222:223]
	v_mul_f32_e32 v220, v104, v172
	v_mul_f32_e32 v221, v105, v173
	v_mul_f32_e32 v219, v110, v178
	v_cvt_pk_bf16_f32 v218, v217, v218
	v_lshl_add_u64 v[222:223], v[222:223], 0, v[224:225]
	v_mul_f32_e32 v227, v111, v179
	v_mul_f32_e32 v228, v107, v175
	v_cvt_pk_bf16_f32 v219, v219, v227
	v_cvt_pk_bf16_f32 v220, v220, v221
	v_cvt_pk_bf16_f32 v221, v226, v228
	global_store_dwordx4 v[222:223], v[218:221], off sc1
	v_mul_f32_e32 v217, v76, v168
	v_mul_f32_e32 v226, v74, v166
	v_mul_f32_e32 v218, v77, v169
	v_mul_f32_e32 v220, v72, v164
	v_mul_f32_e32 v221, v73, v165
	v_mul_f32_e32 v219, v78, v170
	v_cvt_pk_bf16_f32 v218, v217, v218
	v_mul_f32_e32 v227, v79, v171
	v_mul_f32_e32 v228, v75, v167
	v_cvt_pk_bf16_f32 v219, v219, v227
	v_cvt_pk_bf16_f32 v220, v220, v221
	v_cvt_pk_bf16_f32 v221, v226, v228
	global_store_dwordx4 v[222:223], v[218:221], off offset:256 sc1
	v_mul_f32_e32 v217, v100, v160
	v_mul_f32_e32 v226, v98, v158
	v_or_b32_e32 v218, 48, v144
	v_ashrrev_i32_e32 v219, 31, v218
	v_lshlrev_b64 v[222:223], 13, v[218:219]
	v_mul_f32_e32 v220, v96, v156
	v_mul_f32_e32 v218, v101, v161
	v_mul_f32_e32 v221, v97, v157
	v_mul_f32_e32 v219, v102, v162
	v_lshl_add_u64 v[222:223], s[12:13], 0, v[222:223]
	v_mul_f32_e32 v227, v103, v163
	v_mul_f32_e32 v228, v99, v159
	v_cvt_pk_bf16_f32 v218, v217, v218
	v_cvt_pk_bf16_f32 v219, v219, v227
	v_cvt_pk_bf16_f32 v220, v220, v221
	v_cvt_pk_bf16_f32 v221, v226, v228
	v_lshl_add_u64 v[222:223], v[222:223], 0, v[224:225]
	global_store_dwordx4 v[222:223], v[218:221], off sc1
	s_mov_b64 s[44:45], 0
	v_mul_f32_e32 v217, v68, v152
	v_mul_f32_e32 v220, v64, v148
	v_mul_f32_e32 v218, v69, v153
	v_mul_f32_e32 v221, v65, v149
	v_mul_f32_e32 v219, v70, v154
	v_mul_f32_e32 v224, v66, v150
	v_mul_f32_e32 v225, v71, v155
	v_mul_f32_e32 v226, v67, v151
	v_cvt_pk_bf16_f32 v218, v217, v218
	v_cvt_pk_bf16_f32 v219, v219, v225
	v_cvt_pk_bf16_f32 v220, v220, v221
	v_cvt_pk_bf16_f32 v221, v224, v226
	global_store_dwordx4 v[222:223], v[218:221], off offset:256 sc1

;     __device__ __forceinline__ void operator()(f32x4 (&acc)[2][2][4][2], const Unit& u, int wr, int wc, int fr, int fq) const {
;     ...
;         for (int ai = 0; ai < 2; ++ai) {
;             h16x8 gt[4][2];
; #pragma unroll
;             for (int m = 0; m < 4; ++m)
; #pragma unroll
;                 for (int bj = 0; bj < 2; ++bj) gt[m][bj] = *(const h16x8*)(gbase + (size_t)bj * 65536 + (ai * 4 + m) * 4096);
;             if (u.half == 0) {
.LBB0_478:
	v_add_co_u32_e32 v148, vcc, s63, v146
	v_cndmask_b32_e64 v210, 0, 1, s[46:47]
	s_nop 0
	v_addc_co_u32_e32 v149, vcc, 0, v147, vcc
	v_add_co_u32_e32 v152, vcc, s73, v146
	global_load_dwordx4 v[148:151], v[148:149], off nt
	s_nop 0
	v_addc_co_u32_e32 v153, vcc, 0, v147, vcc
	v_add_co_u32_e32 v156, vcc, s67, v146
	global_load_dwordx4 v[152:155], v[152:153], off nt
	s_nop 0
	v_addc_co_u32_e32 v157, vcc, 0, v147, vcc
	v_add_co_u32_e32 v160, vcc, 0x2a000, v146
	global_load_dwordx4 v[156:159], v[156:157], off nt
	s_nop 0
	v_addc_co_u32_e32 v161, vcc, 0, v147, vcc
	v_add_co_u32_e32 v164, vcc, s71, v146
	global_load_dwordx4 v[160:163], v[160:161], off nt
	s_nop 0
	v_addc_co_u32_e32 v165, vcc, 0, v147, vcc
	v_add_co_u32_e32 v168, vcc, 0x2c000, v146
	global_load_dwordx4 v[164:167], v[164:165], off nt
	s_nop 0
	v_addc_co_u32_e32 v169, vcc, 0, v147, vcc
	global_load_dwordx4 v[218:221], v[168:169], off nt
	v_add_co_u32_e32 v168, vcc, 0xe000, v146
	v_cmp_ne_u32_e64 s[4:5], 1, v210
	s_nop 0
	v_addc_co_u32_e32 v169, vcc, 0, v147, vcc
	v_add_co_u32_e32 v146, vcc, 0x2e000, v146
	global_load_dwordx4 v[222:225], v[168:169], off nt
	s_nop 0
	v_addc_co_u32_e32 v147, vcc, 0, v147, vcc
	global_load_dwordx4 v[226:229], v[146:147], off nt
	s_andn2_b64 vcc, exec, s[46:47]
	s_mov_b64 s[44:45], -1
	s_waitcnt vmcnt(7)
	v_cvt_f32_f16_e32 v206, v149
	v_cvt_f32_f16_e32 v208, v148
	v_cvt_f32_f16_e32 v202, v150
	v_cvt_f32_f16_sdwa v209, v148 dst_sel:DWORD dst_unused:UNUSED_PAD src0_sel:WORD_1
	v_cvt_f32_f16_sdwa v203, v150 dst_sel:DWORD dst_unused:UNUSED_PAD src0_sel:WORD_1
	v_cvt_f32_f16_e32 v204, v151
	v_cvt_f32_f16_sdwa v207, v149 dst_sel:DWORD dst_unused:UNUSED_PAD src0_sel:WORD_1
	v_cvt_f32_f16_sdwa v205, v151 dst_sel:DWORD dst_unused:UNUSED_PAD src0_sel:WORD_1
	s_waitcnt vmcnt(6)
	v_cvt_f32_f16_e32 v198, v152
	v_cvt_f32_f16_e32 v194, v154
	v_cvt_f32_f16_sdwa v199, v152 dst_sel:DWORD dst_unused:UNUSED_PAD src0_sel:WORD_1
	v_cvt_f32_f16_sdwa v195, v154 dst_sel:DWORD dst_unused:UNUSED_PAD src0_sel:WORD_1
	v_cvt_f32_f16_e32 v200, v153
	v_cvt_f32_f16_e32 v196, v155
	v_cvt_f32_f16_sdwa v201, v153 dst_sel:DWORD dst_unused:UNUSED_PAD src0_sel:WORD_1
	v_cvt_f32_f16_sdwa v197, v155 dst_sel:DWORD dst_unused:UNUSED_PAD src0_sel:WORD_1
	s_waitcnt vmcnt(5)
	v_cvt_f32_f16_e32 v190, v156
	v_cvt_f32_f16_e32 v186, v158
	v_cvt_f32_f16_sdwa v191, v156 dst_sel:DWORD dst_unused:UNUSED_PAD src0_sel:WORD_1
	v_cvt_f32_f16_sdwa v187, v158 dst_sel:DWORD dst_unused:UNUSED_PAD src0_sel:WORD_1
	v_cvt_f32_f16_e32 v192, v157
	v_cvt_f32_f16_e32 v188, v159
	v_cvt_f32_f16_sdwa v193, v157 dst_sel:DWORD dst_unused:UNUSED_PAD src0_sel:WORD_1
	v_cvt_f32_f16_sdwa v189, v159 dst_sel:DWORD dst_unused:UNUSED_PAD src0_sel:WORD_1
	s_waitcnt vmcnt(4)
	v_cvt_f32_f16_e32 v182, v160
	v_cvt_f32_f16_e32 v178, v162
	v_cvt_f32_f16_sdwa v183, v160 dst_sel:DWORD dst_unused:UNUSED_PAD src0_sel:WORD_1
	v_cvt_f32_f16_sdwa v179, v162 dst_sel:DWORD dst_unused:UNUSED_PAD src0_sel:WORD_1
	v_cvt_f32_f16_e32 v184, v161
	v_cvt_f32_f16_e32 v180, v163
	v_cvt_f32_f16_sdwa v185, v161 dst_sel:DWORD dst_unused:UNUSED_PAD src0_sel:WORD_1
	v_cvt_f32_f16_sdwa v181, v163 dst_sel:DWORD dst_unused:UNUSED_PAD src0_sel:WORD_1
	s_waitcnt vmcnt(3)
	v_cvt_f32_f16_e32 v174, v164
	v_cvt_f32_f16_e32 v170, v166
	v_cvt_f32_f16_sdwa v175, v164 dst_sel:DWORD dst_unused:UNUSED_PAD src0_sel:WORD_1
	v_cvt_f32_f16_sdwa v171, v166 dst_sel:DWORD dst_unused:UNUSED_PAD src0_sel:WORD_1
	v_cvt_f32_f16_e32 v176, v165
	v_cvt_f32_f16_e32 v172, v167
	v_cvt_f32_f16_sdwa v177, v165 dst_sel:DWORD dst_unused:UNUSED_PAD src0_sel:WORD_1
	v_cvt_f32_f16_sdwa v173, v167 dst_sel:DWORD dst_unused:UNUSED_PAD src0_sel:WORD_1
	s_waitcnt vmcnt(2)
	v_cvt_f32_f16_e32 v166, v218
	v_cvt_f32_f16_e32 v162, v220
	v_cvt_f32_f16_sdwa v167, v218 dst_sel:DWORD dst_unused:UNUSED_PAD src0_sel:WORD_1
	v_cvt_f32_f16_sdwa v163, v220 dst_sel:DWORD dst_unused:UNUSED_PAD src0_sel:WORD_1
	v_cvt_f32_f16_e32 v168, v219
	v_cvt_f32_f16_e32 v164, v221
	v_cvt_f32_f16_sdwa v169, v219 dst_sel:DWORD dst_unused:UNUSED_PAD src0_sel:WORD_1
	v_cvt_f32_f16_sdwa v165, v221 dst_sel:DWORD dst_unused:UNUSED_PAD src0_sel:WORD_1
	s_waitcnt vmcnt(1)
	v_cvt_f32_f16_e32 v158, v222
	v_cvt_f32_f16_e32 v154, v224
	v_cvt_f32_f16_sdwa v159, v222 dst_sel:DWORD dst_unused:UNUSED_PAD src0_sel:WORD_1
	v_cvt_f32_f16_sdwa v155, v224 dst_sel:DWORD dst_unused:UNUSED_PAD src0_sel:WORD_1
	v_cvt_f32_f16_e32 v160, v223
	v_cvt_f32_f16_e32 v156, v225
	v_cvt_f32_f16_sdwa v161, v223 dst_sel:DWORD dst_unused:UNUSED_PAD src0_sel:WORD_1
	v_cvt_f32_f16_sdwa v157, v225 dst_sel:DWORD dst_unused:UNUSED_PAD src0_sel:WORD_1
	s_waitcnt vmcnt(0)
	v_cvt_f32_f16_e32 v150, v226
	v_cvt_f32_f16_e32 v146, v228
	v_cvt_f32_f16_sdwa v151, v226 dst_sel:DWORD dst_unused:UNUSED_PAD src0_sel:WORD_1
	v_cvt_f32_f16_sdwa v147, v228 dst_sel:DWORD dst_unused:UNUSED_PAD src0_sel:WORD_1
	v_cvt_f32_f16_e32 v152, v227
	v_cvt_f32_f16_e32 v148, v229
	v_cvt_f32_f16_sdwa v153, v227 dst_sel:DWORD dst_unused:UNUSED_PAD src0_sel:WORD_1
	v_cvt_f32_f16_sdwa v149, v229 dst_sel:DWORD dst_unused:UNUSED_PAD src0_sel:WORD_1
	s_cbranch_vccnz .LBB0_480
;     __device__ __forceinline__ void operator()(f32x4 (&acc)[2][2][4][2], const Unit& u, int wr, int wc, int fr, int fq) const {
;     ...
;                 for (int m = 0; m < 4; ++m) { const size_t row = (size_t)(row0 + ai * HALF + m * 16);
; #pragma unroll
;                     for (int bj = 0; bj < 2; ++bj) { const int col = col0 + bj * HALF;
;                         float o[8];
; #pragma unroll
;                         for (int j = 0; j < 4; ++j) { o[j] = acc[ai][bj][m][0][j] * (float)gt[m][bj][j]; o[4 + j] = acc[ai][bj][m][1][j] * (float)gt[m][bj][4 + j]; }
;                         u32x4 w; w.x = pkg(o[0], o[1]); w.y = pkg(o[2], o[3]); w.z = pkg(o[4], o[5]); w.w = pkg(o[6], o[7]);
;                         *(u32x4*)(MG + row * D + col) = w; } }
	v_lshlrev_b64 v[144:145], 13, v[144:145]
	v_mul_f32_e32 v210, v60, v208
	v_mul_f32_e32 v211, v56, v202
	v_mul_f32_e32 v220, v57, v203
	v_lshl_add_u64 v[144:145], s[12:13], 0, v[144:145]
	v_mul_f32_e32 v217, v61, v209
	v_cvt_pk_bf16_f32 v218, v210, v217
	v_cvt_pk_bf16_f32 v220, v211, v220
	v_lshl_add_u64 v[210:211], v[142:143], 1, v[144:145]
	v_add_co_u32_e32 v142, vcc, s74, v210
	v_mul_f32_e32 v219, v62, v206
	v_mul_f32_e32 v221, v58, v204
	v_mul_f32_e32 v222, v63, v207
	v_mul_f32_e32 v223, v59, v205
	v_addc_co_u32_e32 v143, vcc, 0, v211, vcc
	v_mul_f32_e32 v144, v24, v194
	v_mul_f32_e32 v145, v25, v195
	v_cvt_pk_bf16_f32 v219, v219, v222
	v_cvt_pk_bf16_f32 v221, v221, v223
	v_lshl_add_u64 v[222:223], v[210:211], 0, s[8:9]
	global_store_dwordx4 v[142:143], v[218:221], off sc1
	v_mul_f32_e32 v142, v28, v198
	v_mul_f32_e32 v143, v29, v199
	v_mul_f32_e32 v218, v26, v196
	v_mul_f32_e32 v220, v27, v197
	v_cvt_pk_bf16_f32 v144, v144, v145
	v_cvt_pk_bf16_f32 v145, v218, v220
	v_mul_f32_e32 v217, v30, v200
	v_mul_f32_e32 v219, v31, v201
	v_cvt_pk_bf16_f32 v142, v142, v143
	v_cvt_pk_bf16_f32 v143, v217, v219
	global_store_dwordx4 v[222:223], v[142:145], off offset:256 sc1
	v_mul_f32_e32 v220, v51, v189
	v_mul_f32_e32 v218, v50, v188
	v_mul_f32_e32 v144, v48, v186
	v_mul_f32_e32 v145, v49, v187
	v_cvt_pk_bf16_f32 v144, v144, v145
	v_cvt_pk_bf16_f32 v145, v218, v220
	v_add_co_u32_e32 v220, vcc, s75, v210
	v_mul_f32_e32 v142, v52, v190
	v_mul_f32_e32 v143, v53, v191
	v_addc_co_u32_e32 v221, vcc, 0, v211, vcc
	v_mul_f32_e32 v217, v54, v192
	v_mul_f32_e32 v219, v55, v193
	v_cvt_pk_bf16_f32 v142, v142, v143
	v_cvt_pk_bf16_f32 v143, v217, v219
	global_store_dwordx4 v[220:221], v[142:145], off sc1
	v_lshl_add_u64 v[218:219], v[210:211], 0, s[20:21]
	v_mul_f32_e32 v220, v18, v180
	v_mul_f32_e32 v144, v16, v178
	v_mul_f32_e32 v145, v17, v179
	v_mul_f32_e32 v142, v20, v182
	v_mul_f32_e32 v143, v21, v183
	v_mul_f32_e32 v222, v19, v181
	v_cvt_pk_bf16_f32 v144, v144, v145
	v_cvt_pk_bf16_f32 v145, v220, v222
	v_mul_f32_e32 v217, v22, v184
	v_mul_f32_e32 v221, v23, v185
	v_cvt_pk_bf16_f32 v142, v142, v143
	v_cvt_pk_bf16_f32 v143, v217, v221
	global_store_dwordx4 v[218:219], v[142:145], off offset:256 sc1
	v_mul_f32_e32 v220, v43, v173
	v_mul_f32_e32 v218, v42, v172
	v_mul_f32_e32 v144, v40, v170
	v_mul_f32_e32 v145, v41, v171
	v_mul_f32_e32 v142, v44, v174
	v_mul_f32_e32 v143, v45, v175
	v_cvt_pk_bf16_f32 v144, v144, v145
	v_cvt_pk_bf16_f32 v145, v218, v220
	v_add_co_u32_e32 v220, vcc, s76, v210
	v_mul_f32_e32 v217, v46, v176
	v_mul_f32_e32 v219, v47, v177
	v_cvt_pk_bf16_f32 v142, v142, v143
	v_cvt_pk_bf16_f32 v143, v217, v219
	v_addc_co_u32_e32 v221, vcc, 0, v211, vcc
	global_store_dwordx4 v[220:221], v[142:145], off sc1
	v_lshl_add_u64 v[218:219], v[210:211], 0, s[22:23]
	v_mul_f32_e32 v217, v14, v168
	v_mul_f32_e32 v142, v12, v166
	v_mul_f32_e32 v144, v8, v162
	v_mul_f32_e32 v143, v13, v167
	v_mul_f32_e32 v145, v9, v163
	v_mul_f32_e32 v220, v10, v164
	v_mul_f32_e32 v221, v15, v169
	v_mul_f32_e32 v222, v11, v165
	v_cvt_pk_bf16_f32 v142, v142, v143
	v_cvt_pk_bf16_f32 v143, v217, v221
	v_cvt_pk_bf16_f32 v144, v144, v145
	v_cvt_pk_bf16_f32 v145, v220, v222
	global_store_dwordx4 v[218:219], v[142:145], off offset:256 sc1
	v_mul_f32_e32 v218, v34, v156
	v_mul_f32_e32 v219, v39, v161
	v_mul_f32_e32 v142, v36, v158
	v_mul_f32_e32 v144, v32, v154
	v_mul_f32_e32 v143, v37, v159
	v_mul_f32_e32 v145, v33, v155
	v_mul_f32_e32 v217, v38, v160
	v_mul_f32_e32 v220, v35, v157
	v_cvt_pk_bf16_f32 v142, v142, v143
	v_cvt_pk_bf16_f32 v143, v217, v219
	v_cvt_pk_bf16_f32 v144, v144, v145
	v_cvt_pk_bf16_f32 v145, v218, v220
	v_lshl_add_u64 v[218:219], v[210:211], 0, s[24:25]
	v_add_co_u32_e32 v210, vcc, s77, v210
	s_mov_b64 s[44:45], 0
	s_nop 0
	v_addc_co_u32_e32 v211, vcc, 0, v211, vcc
	global_store_dwordx4 v[210:211], v[142:145], off sc1
	v_mul_f32_e32 v210, v6, v152
	v_mul_f32_e32 v211, v2, v148
	v_mul_f32_e32 v142, v4, v150
	v_mul_f32_e32 v144, v0, v146
	v_mul_f32_e32 v143, v5, v151
	v_mul_f32_e32 v145, v1, v147
	v_mul_f32_e32 v217, v7, v153
	v_mul_f32_e32 v220, v3, v149
	v_cvt_pk_bf16_f32 v142, v142, v143
	v_cvt_pk_bf16_f32 v143, v210, v217
	v_cvt_pk_bf16_f32 v144, v144, v145
	v_cvt_pk_bf16_f32 v145, v211, v220
	global_store_dwordx4 v[218:219], v[142:145], off offset:256 sc1
